# P3 idle-tail weight copies rebalanced: W_ba/W_bb/W_bc transpose items moved from waves 0..255 to waves 1280..1535 of the copy team
# speedup vs baseline: 1.0128x; 1.0058x over previous
;     ...
;     const int nblk = nb1 - nb0, nitems = (K / 64) * nblk;
;     for (int item = gw; item < nitems; item += ngw) {
;         const int kb = item / nblk, nb = nb0 + item % nblk, k0 = 64 * kb, n0 = 32 * nb;
;         float tv[32];
; #pragma unroll
;         for (int i = 0; i < 32; ++i) { const int kk = 2 * i + (lane >> 5); tv[i] = W[(size_t)(k0 + kk) * N + n0 + (lane & 31)]; }
; #pragma unroll
;         for (int i = 0; i < 32; ++i) { const int kk = 2 * i + (lane >> 5); float v = tv[i]; if (gk) v *= gk[k0 + kk]; scr[kk * 33 + (lane & 31)] = v; }
; __global__ void __launch_bounds__(512, 2) fwd_mega(Args args) {
;     ...
;             transpose_mat(args.in[23], 512, 1024, nullptr, 0, wBA, nullptr, scr, gw2, ngw2, lane);
;             transpose_mat(args.in[24], 512, 1024, nullptr, 0, wBB, nullptr, scr, gw2, ngw2, lane);
;             transpose_mat(args.in[25], 512, 1024, nullptr, 0, wBC, nullptr, scr, gw2, ngw2, lane);
.LBB0_1071:
	s_add_i32 s100, s13, 0xfffffb00
	s_cmp_lt_i32 s100, 0
	s_cselect_b32 s101, 0x600, 0
	s_add_i32 s100, s100, s101
	s_nop 0
	s_nop 0
	s_cmpk_gt_i32 s100, 0xff
	s_cbranch_scc1 .LBB0_1078
	s_add_u32 s5, s68, 0x1f00000
	s_addc_u32 s6, s69, 0
	v_mov_b32_e32 v5, 0
	v_lshlrev_b32_e32 v14, 9, v36
	v_lshlrev_b32_e32 v16, 9, v49
	v_lshlrev_b32_e32 v18, 9, v50
	v_lshlrev_b32_e32 v20, 9, v51
	s_lshl_b32 s4, s100, 5
	v_lshl_add_u64 v[22:23], s[66:67], 0, v[4:5]
	v_mov_b32_e32 v3, v5
	v_lshlrev_b32_e32 v14, 1, v14
	v_mov_b32_e32 v15, v5
	v_lshlrev_b32_e32 v16, 1, v16
	v_mov_b32_e32 v17, v5
	v_lshlrev_b32_e32 v18, 1, v18
	v_mov_b32_e32 v19, v5
	v_lshlrev_b32_e32 v20, 1, v20
	v_mov_b32_e32 v21, v5
	v_add_u32_e32 v1, 0x400, v35
	v_add_u32_e32 v5, 0x800, v35
	v_add_u32_e32 v7, 0xc00, v35
	v_add_u32_e32 v9, 0x1000, v35
	v_add_u32_e32 v11, 0x1400, v35
	v_add_u32_e32 v13, 0x1800, v35
	v_add_u32_e32 v24, 0x1c00, v35
	s_mov_b32 s7, s4
	s_mov_b32 s8, s100
.LBB0_1073:
	s_ashr_i32 s0, s8, 31
	s_lshr_b32 s0, s0, 27
	s_add_i32 s0, s8, s0
	s_ashr_i32 s1, s0, 5
	s_lshl_b32 s0, s1, 6
	s_lshl_b32 s1, s1, 10
	v_or_b32_e32 v26, s0, v0
	s_sub_i32 s2, s7, s1
	v_or_b32_e32 v28, 2, v26
	v_or_b32_e32 v54, 12, v26
	v_or_b32_e32 v56, 14, v26
	v_or_b32_e32 v58, 16, v26
	v_or_b32_e32 v60, 18, v26
	v_or_b32_e32 v62, 20, v26
	v_or_b32_e32 v64, 22, v26
	v_or_b32_e32 v66, 24, v26
	v_or_b32_e32 v68, 26, v26
	v_or_b32_e32 v70, 28, v26
	v_or_b32_e32 v72, 30, v26
	v_or_b32_e32 v74, 32, v26
	v_or_b32_e32 v76, 34, v26
	v_or_b32_e32 v78, 36, v26
	s_ashr_i32 s3, s2, 31
	v_ashrrev_i32_e32 v27, 31, v26
	v_or_b32_e32 v30, 4, v26
	v_or_b32_e32 v32, 6, v26
	v_or_b32_e32 v50, 8, v26
	v_or_b32_e32 v52, 10, v26
	v_or_b32_e32 v80, 38, v26
	v_or_b32_e32 v82, 40, v26
	v_or_b32_e32 v84, 42, v26
	v_or_b32_e32 v86, 44, v26
	v_or_b32_e32 v88, 46, v26
	v_or_b32_e32 v90, 48, v26
	v_or_b32_e32 v92, 50, v26
	v_or_b32_e32 v94, 52, v26
	v_or_b32_e32 v96, 54, v26
	v_or_b32_e32 v98, 56, v26
	v_or_b32_e32 v100, 58, v26
	v_or_b32_e32 v102, 60, v26
	v_or_b32_e32 v104, 62, v26
	v_ashrrev_i32_e32 v29, 31, v28
	v_ashrrev_i32_e32 v55, 31, v54
	v_ashrrev_i32_e32 v57, 31, v56
	v_ashrrev_i32_e32 v59, 31, v58
	v_ashrrev_i32_e32 v61, 31, v60
	v_ashrrev_i32_e32 v63, 31, v62
	v_ashrrev_i32_e32 v65, 31, v64
	v_ashrrev_i32_e32 v67, 31, v66
	v_ashrrev_i32_e32 v69, 31, v68
	v_ashrrev_i32_e32 v71, 31, v70
	v_ashrrev_i32_e32 v73, 31, v72
	v_ashrrev_i32_e32 v75, 31, v74
	v_ashrrev_i32_e32 v77, 31, v76
	v_ashrrev_i32_e32 v79, 31, v78
	v_lshl_add_u64 v[106:107], s[2:3], 2, v[22:23]
	v_lshlrev_b64 v[26:27], 12, v[26:27]
	v_ashrrev_i32_e32 v31, 31, v30
	v_ashrrev_i32_e32 v33, 31, v32
	v_ashrrev_i32_e32 v51, 31, v50
	v_ashrrev_i32_e32 v53, 31, v52
	v_ashrrev_i32_e32 v81, 31, v80
	v_ashrrev_i32_e32 v83, 31, v82
	v_ashrrev_i32_e32 v85, 31, v84
	v_ashrrev_i32_e32 v87, 31, v86
	v_ashrrev_i32_e32 v89, 31, v88
	v_ashrrev_i32_e32 v91, 31, v90
	v_ashrrev_i32_e32 v93, 31, v92
	v_ashrrev_i32_e32 v95, 31, v94
	v_ashrrev_i32_e32 v97, 31, v96
	v_ashrrev_i32_e32 v99, 31, v98
	v_ashrrev_i32_e32 v101, 31, v100
	v_ashrrev_i32_e32 v103, 31, v102
	v_ashrrev_i32_e32 v105, 31, v104
	v_lshlrev_b64 v[28:29], 12, v[28:29]
	v_lshlrev_b64 v[54:55], 12, v[54:55]
	v_lshlrev_b64 v[56:57], 12, v[56:57]
	v_lshlrev_b64 v[58:59], 12, v[58:59]
	v_lshlrev_b64 v[60:61], 12, v[60:61]
	v_lshlrev_b64 v[62:63], 12, v[62:63]
	v_lshlrev_b64 v[64:65], 12, v[64:65]
	v_lshlrev_b64 v[66:67], 12, v[66:67]
	v_lshlrev_b64 v[68:69], 12, v[68:69]
	v_lshlrev_b64 v[70:71], 12, v[70:71]
	v_lshlrev_b64 v[72:73], 12, v[72:73]
	v_lshlrev_b64 v[74:75], 12, v[74:75]
	v_lshlrev_b64 v[76:77], 12, v[76:77]
	v_lshlrev_b64 v[78:79], 12, v[78:79]
	v_lshl_add_u64 v[26:27], v[106:107], 0, v[26:27]
	v_lshlrev_b64 v[30:31], 12, v[30:31]
	v_lshlrev_b64 v[32:33], 12, v[32:33]
	v_lshlrev_b64 v[50:51], 12, v[50:51]
	v_lshlrev_b64 v[52:53], 12, v[52:53]
	v_lshlrev_b64 v[80:81], 12, v[80:81]
	v_lshlrev_b64 v[82:83], 12, v[82:83]
	v_lshlrev_b64 v[84:85], 12, v[84:85]
	v_lshlrev_b64 v[86:87], 12, v[86:87]
	v_lshlrev_b64 v[88:89], 12, v[88:89]
	v_lshlrev_b64 v[90:91], 12, v[90:91]
	v_lshlrev_b64 v[92:93], 12, v[92:93]
	v_lshlrev_b64 v[94:95], 12, v[94:95]
	v_lshlrev_b64 v[96:97], 12, v[96:97]
	v_lshlrev_b64 v[98:99], 12, v[98:99]
	v_lshlrev_b64 v[100:101], 12, v[100:101]
	v_lshlrev_b64 v[102:103], 12, v[102:103]
	v_lshlrev_b64 v[104:105], 12, v[104:105]
	v_lshl_add_u64 v[28:29], v[106:107], 0, v[28:29]
	v_lshl_add_u64 v[54:55], v[106:107], 0, v[54:55]
	v_lshl_add_u64 v[56:57], v[106:107], 0, v[56:57]
	v_lshl_add_u64 v[58:59], v[106:107], 0, v[58:59]
	v_lshl_add_u64 v[60:61], v[106:107], 0, v[60:61]
	v_lshl_add_u64 v[62:63], v[106:107], 0, v[62:63]
	v_lshl_add_u64 v[64:65], v[106:107], 0, v[64:65]
	v_lshl_add_u64 v[66:67], v[106:107], 0, v[66:67]
	v_lshl_add_u64 v[68:69], v[106:107], 0, v[68:69]
	v_lshl_add_u64 v[70:71], v[106:107], 0, v[70:71]
	v_lshl_add_u64 v[72:73], v[106:107], 0, v[72:73]
	v_lshl_add_u64 v[74:75], v[106:107], 0, v[74:75]
	v_lshl_add_u64 v[76:77], v[106:107], 0, v[76:77]
	v_lshl_add_u64 v[78:79], v[106:107], 0, v[78:79]
	v_lshl_add_u64 v[30:31], v[106:107], 0, v[30:31]
	v_lshl_add_u64 v[32:33], v[106:107], 0, v[32:33]
	v_lshl_add_u64 v[50:51], v[106:107], 0, v[50:51]
	v_lshl_add_u64 v[52:53], v[106:107], 0, v[52:53]
	v_lshl_add_u64 v[80:81], v[106:107], 0, v[80:81]
	v_lshl_add_u64 v[82:83], v[106:107], 0, v[82:83]
	v_lshl_add_u64 v[84:85], v[106:107], 0, v[84:85]
	v_lshl_add_u64 v[86:87], v[106:107], 0, v[86:87]
	v_lshl_add_u64 v[88:89], v[106:107], 0, v[88:89]
	v_lshl_add_u64 v[90:91], v[106:107], 0, v[90:91]
	v_lshl_add_u64 v[92:93], v[106:107], 0, v[92:93]
; #define LAS __attribute__((address_space(3)))
; DI unsigned pk2(float lo, float hi) { typedef float v2f __attribute__((ext_vector_type(2))); typedef __bf16 v2b __attribute__((ext_vector_type(2))); v2f v = {lo, hi}; v2b b = __builtin_convertvector(v, v2b); return __builtin_bit_cast(unsigned, b); }
;     ...
;         for (int i = 0; i < 32; ++i) { const int kk = 2 * i + (lane >> 5); tv[i] = W[(size_t)(k0 + kk) * N + n0 + (lane & 31)]; }
; #pragma unroll
;         for (int i = 0; i < 32; ++i) { const int kk = 2 * i + (lane >> 5); float v = tv[i]; if (gk) v *= gk[k0 + kk]; scr[kk * 33 + (lane & 31)] = v; }
;         asm volatile("s_waitcnt lgkmcnt(0)" ::: "memory");
;         bf16_t* dst = dest_rows(mode, n0, K, d0, d1);
;         const int c = lane & 7;
; #pragma unroll
;         for (int jj = 0; jj < 4; ++jj) { const int n = (lane >> 3) + 8 * jj; const LAS float* s = scr + (8 * c) * 33 + n;
;             u32x4 o; o.x = pk2(s[0 * 33], s[1 * 33]); o.y = pk2(s[2 * 33], s[3 * 33]); o.z = pk2(s[4 * 33], s[5 * 33]); o.w = pk2(s[6 * 33], s[7 * 33]);
;             *(u32x4*)(dst + (size_t)n * K + k0 + 8 * c) = o; }
;         asm volatile("s_waitcnt lgkmcnt(0)" ::: "memory");
;     }
	v_lshl_add_u64 v[94:95], v[106:107], 0, v[94:95]
	v_lshl_add_u64 v[96:97], v[106:107], 0, v[96:97]
	v_lshl_add_u64 v[98:99], v[106:107], 0, v[98:99]
	v_lshl_add_u64 v[100:101], v[106:107], 0, v[100:101]
	v_lshl_add_u64 v[102:103], v[106:107], 0, v[102:103]
	v_lshl_add_u64 v[104:105], v[106:107], 0, v[104:105]
	global_load_dword v25, v[26:27], off
	s_nop 0
	global_load_dword v26, v[28:29], off
	global_load_dword v27, v[30:31], off
	s_nop 0
	global_load_dword v28, v[32:33], off
	global_load_dword v29, v[50:51], off
	global_load_dword v49, v[52:53], off
	s_nop 0
	global_load_dword v54, v[54:55], off
	s_nop 0
	global_load_dword v55, v[56:57], off
	s_nop 0
	global_load_dword v56, v[58:59], off
	global_load_dword v57, v[60:61], off
	s_nop 0
	global_load_dword v58, v[62:63], off
	global_load_dword v59, v[64:65], off
	global_load_dword v60, v[66:67], off
	global_load_dword v61, v[68:69], off
	s_nop 0
	global_load_dword v62, v[70:71], off
	global_load_dword v63, v[72:73], off
	global_load_dword v64, v[74:75], off
	global_load_dword v65, v[76:77], off
	global_load_dword v66, v[78:79], off
	global_load_dword v67, v[80:81], off
	global_load_dword v68, v[82:83], off
	global_load_dword v69, v[84:85], off
	global_load_dword v70, v[86:87], off
	global_load_dword v71, v[88:89], off
	global_load_dword v72, v[90:91], off
	global_load_dword v73, v[92:93], off
	global_load_dword v74, v[94:95], off
	global_load_dword v75, v[96:97], off
	global_load_dword v76, v[98:99], off
	global_load_dword v77, v[100:101], off
	global_load_dword v78, v[102:103], off
	global_load_dword v79, v[104:105], off
	s_lshl_b64 s[2:3], s[2:3], 10
	s_waitcnt vmcnt(0)
	ds_write2_b32 v35, v25, v26 offset1:66
	ds_write2_b32 v35, v27, v28 offset0:132 offset1:198
	ds_write2_b32 v1, v29, v49 offset0:8 offset1:74
	ds_write2_b32 v1, v54, v55 offset0:140 offset1:206
	ds_write2_b32 v5, v56, v57 offset0:16 offset1:82
	ds_write2_b32 v5, v58, v59 offset0:148 offset1:214
	ds_write2_b32 v7, v60, v61 offset0:24 offset1:90
	ds_write2_b32 v7, v62, v63 offset0:156 offset1:222
	ds_write2_b32 v9, v64, v65 offset0:32 offset1:98
	ds_write2_b32 v9, v66, v67 offset0:164 offset1:230
	ds_write2_b32 v11, v68, v69 offset0:40 offset1:106
	ds_write2_b32 v11, v70, v71 offset0:172 offset1:238
	ds_write2_b32 v13, v72, v73 offset0:48 offset1:114
	ds_write2_b32 v13, v74, v75 offset0:180 offset1:246
	ds_write2_b32 v24, v76, v77 offset0:56 offset1:122
	ds_write2_b32 v24, v78, v79 offset0:188 offset1:254
	s_add_u32 s2, s5, s2
	s_waitcnt lgkmcnt(0)
	s_addc_u32 s3, s6, s3
	s_ashr_i32 s1, s0, 31
	ds_read_b32 v25, v34
	ds_read_b32 v26, v34 offset:132
	ds_read_b32 v27, v34 offset:264
	ds_read_b32 v28, v34 offset:396
	ds_read_b32 v29, v34 offset:528
	ds_read_b32 v49, v34 offset:660
	ds_read_b32 v54, v34 offset:792
	ds_read_b32 v55, v34 offset:924
	s_lshl_b64 s[0:1], s[0:1], 1
	s_add_u32 s0, s2, s0
	s_addc_u32 s1, s3, s1
	v_lshl_add_u64 v[30:31], s[0:1], 0, v[2:3]
	v_lshl_add_u64 v[32:33], v[30:31], 0, v[14:15]
	s_waitcnt lgkmcnt(0)
	v_cvt_pk_bf16_f32 v26, v25, v26
	v_cvt_pk_bf16_f32 v27, v27, v28
	v_cvt_pk_bf16_f32 v28, v29, v49
	v_cvt_pk_bf16_f32 v29, v54, v55
	flat_store_dwordx4 v[32:33], v[26:29]
	ds_read_b32 v25, v34 offset:32
	ds_read_b32 v26, v34 offset:164
	ds_read_b32 v27, v34 offset:296
	ds_read_b32 v28, v34 offset:428
	ds_read_b32 v29, v34 offset:560
	ds_read_b32 v32, v34 offset:692
	ds_read_b32 v33, v34 offset:824
	ds_read_b32 v49, v34 offset:956
	v_lshl_add_u64 v[50:51], v[30:31], 0, v[16:17]
	s_waitcnt lgkmcnt(0)
	v_cvt_pk_bf16_f32 v26, v25, v26
	v_cvt_pk_bf16_f32 v27, v27, v28
	v_cvt_pk_bf16_f32 v28, v29, v32
	v_cvt_pk_bf16_f32 v29, v33, v49
	flat_store_dwordx4 v[50:51], v[26:29]
	ds_read_b32 v25, v34 offset:64
	ds_read_b32 v26, v34 offset:196
	ds_read_b32 v27, v34 offset:328
	ds_read_b32 v28, v34 offset:460
	ds_read_b32 v29, v34 offset:592
	ds_read_b32 v32, v34 offset:724
	ds_read_b32 v33, v34 offset:856
	ds_read_b32 v49, v34 offset:988
	v_lshl_add_u64 v[52:53], v[30:31], 0, v[18:19]
	s_waitcnt lgkmcnt(0)
	v_cvt_pk_bf16_f32 v26, v25, v26
	v_cvt_pk_bf16_f32 v27, v27, v28
	v_cvt_pk_bf16_f32 v28, v29, v32
	v_cvt_pk_bf16_f32 v29, v33, v49
	flat_store_dwordx4 v[52:53], v[26:29]
	ds_read_b32 v25, v34 offset:96
	ds_read_b32 v26, v34 offset:228
	ds_read_b32 v27, v34 offset:360
	ds_read_b32 v28, v34 offset:492
	ds_read_b32 v29, v34 offset:624
	ds_read_b32 v32, v34 offset:756
	ds_read_b32 v33, v34 offset:888
	ds_read_b32 v49, v34 offset:1020
	v_lshl_add_u64 v[30:31], v[30:31], 0, v[20:21]
	s_waitcnt lgkmcnt(0)
	v_cvt_pk_bf16_f32 v26, v25, v26
	v_cvt_pk_bf16_f32 v27, v27, v28
	v_cvt_pk_bf16_f32 v28, v29, v32
	v_cvt_pk_bf16_f32 v29, v33, v49
	flat_store_dwordx4 v[30:31], v[26:29]
	s_waitcnt lgkmcnt(0)
	s_add_i32 s2, s8, 0x600
	s_add_i32 s7, s7, 0xc000
	s_cmpk_lt_i32 s8, 0xfb00
	s_mov_b32 s8, s2
	s_cbranch_scc1 .LBB0_1073
	v_mov_b32_e32 v3, 0
	v_readlane_b32 s16, v249, 1
	v_mov_b32_e32 v5, v3
	v_readlane_b32 s17, v249, 2
	s_add_u32 s5, s68, 0x2000000
	s_addc_u32 s6, s69, 0
	v_lshl_add_u64 v[22:23], s[16:17], 0, v[4:5]
	s_mov_b32 s7, s4
	s_mov_b32 s8, s100
	v_readlane_b32 s18, v249, 3
	v_readlane_b32 s19, v249, 4
	v_readlane_b32 s20, v249, 5
	v_readlane_b32 s21, v249, 6
	v_readlane_b32 s22, v249, 7
	v_readlane_b32 s23, v249, 8
	v_readlane_b32 s24, v249, 9
	v_readlane_b32 s25, v249, 10
	v_readlane_b32 s26, v249, 11
	v_readlane_b32 s27, v249, 12
	v_readlane_b32 s28, v249, 13
	v_readlane_b32 s29, v249, 14
	v_readlane_b32 s30, v249, 15
	v_readlane_b32 s31, v249, 16
;     ...
;     for (int item = gw; item < nitems; item += ngw) {
;         const int kb = item / nblk, nb = nb0 + item % nblk, k0 = 64 * kb, n0 = 32 * nb;
;         float tv[32];
; #pragma unroll
;         for (int i = 0; i < 32; ++i) { const int kk = 2 * i + (lane >> 5); tv[i] = W[(size_t)(k0 + kk) * N + n0 + (lane & 31)]; }
.LBB0_1075:
	s_ashr_i32 s0, s8, 31
	s_lshr_b32 s0, s0, 27
	s_add_i32 s0, s8, s0
	s_ashr_i32 s1, s0, 5
	s_lshl_b32 s0, s1, 6
	s_lshl_b32 s1, s1, 10
	v_or_b32_e32 v24, s0, v0
	s_sub_i32 s2, s7, s1
	v_or_b32_e32 v26, 2, v24
	v_or_b32_e32 v52, 12, v24
	v_or_b32_e32 v54, 14, v24
	v_or_b32_e32 v56, 16, v24
	v_or_b32_e32 v58, 18, v24
	v_or_b32_e32 v60, 20, v24
	v_or_b32_e32 v62, 22, v24
	v_or_b32_e32 v64, 24, v24
	v_or_b32_e32 v66, 26, v24
	v_or_b32_e32 v68, 28, v24
	v_or_b32_e32 v70, 30, v24
	v_or_b32_e32 v72, 32, v24
	s_ashr_i32 s3, s2, 31
	v_ashrrev_i32_e32 v25, 31, v24
	v_or_b32_e32 v28, 4, v24
	v_or_b32_e32 v30, 6, v24
	v_or_b32_e32 v32, 8, v24
	v_or_b32_e32 v50, 10, v24
	v_or_b32_e32 v74, 34, v24
	v_or_b32_e32 v76, 36, v24
	v_or_b32_e32 v78, 38, v24
	v_or_b32_e32 v80, 40, v24
	v_or_b32_e32 v82, 42, v24
	v_or_b32_e32 v84, 44, v24
	v_or_b32_e32 v86, 46, v24
	v_or_b32_e32 v88, 48, v24
	v_or_b32_e32 v90, 50, v24
	v_or_b32_e32 v92, 52, v24
	v_or_b32_e32 v94, 54, v24
	v_or_b32_e32 v96, 56, v24
	v_or_b32_e32 v98, 58, v24
	v_or_b32_e32 v100, 60, v24
	v_or_b32_e32 v102, 62, v24
	v_ashrrev_i32_e32 v27, 31, v26
	v_ashrrev_i32_e32 v53, 31, v52
	v_ashrrev_i32_e32 v55, 31, v54
	v_ashrrev_i32_e32 v57, 31, v56
	v_ashrrev_i32_e32 v59, 31, v58
	v_ashrrev_i32_e32 v61, 31, v60
	v_ashrrev_i32_e32 v63, 31, v62
	v_ashrrev_i32_e32 v65, 31, v64
	v_ashrrev_i32_e32 v67, 31, v66
	v_ashrrev_i32_e32 v69, 31, v68
	v_ashrrev_i32_e32 v71, 31, v70
	v_ashrrev_i32_e32 v73, 31, v72
	v_lshl_add_u64 v[104:105], s[2:3], 2, v[22:23]
	v_lshlrev_b64 v[24:25], 12, v[24:25]
	v_ashrrev_i32_e32 v29, 31, v28
	v_ashrrev_i32_e32 v31, 31, v30
	v_ashrrev_i32_e32 v33, 31, v32
	v_ashrrev_i32_e32 v51, 31, v50
	v_ashrrev_i32_e32 v75, 31, v74
	v_ashrrev_i32_e32 v77, 31, v76
	v_ashrrev_i32_e32 v79, 31, v78
	v_ashrrev_i32_e32 v81, 31, v80
	v_ashrrev_i32_e32 v83, 31, v82
	v_ashrrev_i32_e32 v85, 31, v84
	v_ashrrev_i32_e32 v87, 31, v86
	v_ashrrev_i32_e32 v89, 31, v88
	v_ashrrev_i32_e32 v91, 31, v90
	v_ashrrev_i32_e32 v93, 31, v92
	v_ashrrev_i32_e32 v95, 31, v94
	v_ashrrev_i32_e32 v97, 31, v96
	v_ashrrev_i32_e32 v99, 31, v98
	v_ashrrev_i32_e32 v101, 31, v100
	v_ashrrev_i32_e32 v103, 31, v102
	v_lshlrev_b64 v[26:27], 12, v[26:27]
	v_lshlrev_b64 v[52:53], 12, v[52:53]
	v_lshlrev_b64 v[54:55], 12, v[54:55]
	v_lshlrev_b64 v[56:57], 12, v[56:57]
	v_lshlrev_b64 v[58:59], 12, v[58:59]
	v_lshlrev_b64 v[60:61], 12, v[60:61]
	v_lshlrev_b64 v[62:63], 12, v[62:63]
	v_lshlrev_b64 v[64:65], 12, v[64:65]
	v_lshlrev_b64 v[66:67], 12, v[66:67]
	v_lshlrev_b64 v[68:69], 12, v[68:69]
	v_lshlrev_b64 v[70:71], 12, v[70:71]
	v_lshlrev_b64 v[72:73], 12, v[72:73]
	v_lshl_add_u64 v[24:25], v[104:105], 0, v[24:25]
	v_lshlrev_b64 v[28:29], 12, v[28:29]
	v_lshlrev_b64 v[30:31], 12, v[30:31]
	v_lshlrev_b64 v[32:33], 12, v[32:33]
	v_lshlrev_b64 v[50:51], 12, v[50:51]
	v_lshlrev_b64 v[74:75], 12, v[74:75]
	v_lshlrev_b64 v[76:77], 12, v[76:77]
	v_lshlrev_b64 v[78:79], 12, v[78:79]
	v_lshlrev_b64 v[80:81], 12, v[80:81]
	v_lshlrev_b64 v[82:83], 12, v[82:83]
	v_lshlrev_b64 v[84:85], 12, v[84:85]
	v_lshlrev_b64 v[86:87], 12, v[86:87]
	v_lshlrev_b64 v[88:89], 12, v[88:89]
	v_lshlrev_b64 v[90:91], 12, v[90:91]
	v_lshlrev_b64 v[92:93], 12, v[92:93]
	v_lshlrev_b64 v[94:95], 12, v[94:95]
	v_lshlrev_b64 v[96:97], 12, v[96:97]
	v_lshlrev_b64 v[98:99], 12, v[98:99]
	v_lshlrev_b64 v[100:101], 12, v[100:101]
	v_lshlrev_b64 v[102:103], 12, v[102:103]
	v_lshl_add_u64 v[26:27], v[104:105], 0, v[26:27]
	v_lshl_add_u64 v[52:53], v[104:105], 0, v[52:53]
	v_lshl_add_u64 v[54:55], v[104:105], 0, v[54:55]
	v_lshl_add_u64 v[56:57], v[104:105], 0, v[56:57]
	v_lshl_add_u64 v[58:59], v[104:105], 0, v[58:59]
	v_lshl_add_u64 v[60:61], v[104:105], 0, v[60:61]
	v_lshl_add_u64 v[62:63], v[104:105], 0, v[62:63]
	v_lshl_add_u64 v[64:65], v[104:105], 0, v[64:65]
	v_lshl_add_u64 v[66:67], v[104:105], 0, v[66:67]
	v_lshl_add_u64 v[68:69], v[104:105], 0, v[68:69]
	v_lshl_add_u64 v[70:71], v[104:105], 0, v[70:71]
	v_lshl_add_u64 v[72:73], v[104:105], 0, v[72:73]
	v_lshl_add_u64 v[28:29], v[104:105], 0, v[28:29]
	v_lshl_add_u64 v[30:31], v[104:105], 0, v[30:31]
	v_lshl_add_u64 v[32:33], v[104:105], 0, v[32:33]
	v_lshl_add_u64 v[50:51], v[104:105], 0, v[50:51]
	v_lshl_add_u64 v[74:75], v[104:105], 0, v[74:75]
	v_lshl_add_u64 v[76:77], v[104:105], 0, v[76:77]
	v_lshl_add_u64 v[78:79], v[104:105], 0, v[78:79]
	v_lshl_add_u64 v[80:81], v[104:105], 0, v[80:81]
	v_lshl_add_u64 v[82:83], v[104:105], 0, v[82:83]
	v_lshl_add_u64 v[84:85], v[104:105], 0, v[84:85]
	v_lshl_add_u64 v[86:87], v[104:105], 0, v[86:87]
	v_lshl_add_u64 v[88:89], v[104:105], 0, v[88:89]
	v_lshl_add_u64 v[90:91], v[104:105], 0, v[90:91]
	v_lshl_add_u64 v[92:93], v[104:105], 0, v[92:93]
	v_lshl_add_u64 v[94:95], v[104:105], 0, v[94:95]
	v_lshl_add_u64 v[96:97], v[104:105], 0, v[96:97]
	v_lshl_add_u64 v[98:99], v[104:105], 0, v[98:99]
	v_lshl_add_u64 v[100:101], v[104:105], 0, v[100:101]
	v_lshl_add_u64 v[102:103], v[104:105], 0, v[102:103]
	global_load_dword v1, v[24:25], off
	global_load_dword v5, v[26:27], off
	global_load_dword v7, v[28:29], off
	global_load_dword v9, v[30:31], off
	global_load_dword v11, v[32:33], off
	global_load_dword v13, v[50:51], off
	global_load_dword v24, v[52:53], off
	global_load_dword v25, v[54:55], off
	global_load_dword v26, v[56:57], off
	global_load_dword v27, v[58:59], off
	global_load_dword v49, v[60:61], off
	s_nop 0
	global_load_dword v52, v[62:63], off
	global_load_dword v53, v[64:65], off
	global_load_dword v54, v[66:67], off
	global_load_dword v55, v[68:69], off
	global_load_dword v56, v[70:71], off
	global_load_dword v57, v[72:73], off
	global_load_dword v58, v[74:75], off
	global_load_dword v59, v[76:77], off
	global_load_dword v60, v[78:79], off
	global_load_dword v61, v[80:81], off
	global_load_dword v62, v[82:83], off
	global_load_dword v63, v[84:85], off
	global_load_dword v64, v[86:87], off
	global_load_dword v65, v[88:89], off
	global_load_dword v66, v[90:91], off
	global_load_dword v67, v[92:93], off
	global_load_dword v68, v[94:95], off
	global_load_dword v69, v[96:97], off
	global_load_dword v70, v[98:99], off
	global_load_dword v71, v[100:101], off
	global_load_dword v72, v[102:103], off
	s_lshl_b64 s[2:3], s[2:3], 10
	s_add_u32 s2, s5, s2
	s_addc_u32 s3, s6, s3
	s_ashr_i32 s1, s0, 31
	s_lshl_b64 s[0:1], s[0:1], 1
	s_add_u32 s0, s2, s0
	v_add_u32_e32 v73, 0x400, v35
	v_add_u32_e32 v74, 0x800, v35
	v_add_u32_e32 v75, 0xc00, v35
	v_add_u32_e32 v76, 0x1000, v35
	v_add_u32_e32 v77, 0x1400, v35
	v_add_u32_e32 v78, 0x1800, v35
	v_add_u32_e32 v79, 0x1c00, v35
	s_addc_u32 s1, s3, s1
	s_waitcnt vmcnt(0)
; #define LAS __attribute__((address_space(3)))
; DI unsigned pk2(float lo, float hi) { typedef float v2f __attribute__((ext_vector_type(2))); typedef __bf16 v2b __attribute__((ext_vector_type(2))); v2f v = {lo, hi}; v2b b = __builtin_convertvector(v, v2b); return __builtin_bit_cast(unsigned, b); }
;     ...
;         for (int i = 0; i < 32; ++i) { const int kk = 2 * i + (lane >> 5); float v = tv[i]; if (gk) v *= gk[k0 + kk]; scr[kk * 33 + (lane & 31)] = v; }
;         asm volatile("s_waitcnt lgkmcnt(0)" ::: "memory");
;         bf16_t* dst = dest_rows(mode, n0, K, d0, d1);
;         const int c = lane & 7;
; #pragma unroll
;         for (int jj = 0; jj < 4; ++jj) { const int n = (lane >> 3) + 8 * jj; const LAS float* s = scr + (8 * c) * 33 + n;
;             u32x4 o; o.x = pk2(s[0 * 33], s[1 * 33]); o.y = pk2(s[2 * 33], s[3 * 33]); o.z = pk2(s[4 * 33], s[5 * 33]); o.w = pk2(s[6 * 33], s[7 * 33]);
;             *(u32x4*)(dst + (size_t)n * K + k0 + 8 * c) = o; }
;         asm volatile("s_waitcnt lgkmcnt(0)" ::: "memory");
;     }
	ds_write2_b32 v35, v1, v5 offset1:66
	ds_write2_b32 v35, v7, v9 offset0:132 offset1:198
	ds_write2_b32 v73, v11, v13 offset0:8 offset1:74
	ds_write2_b32 v73, v24, v25 offset0:140 offset1:206
	ds_write2_b32 v74, v26, v27 offset0:16 offset1:82
	ds_write2_b32 v74, v49, v52 offset0:148 offset1:214
	ds_write2_b32 v75, v53, v54 offset0:24 offset1:90
	ds_write2_b32 v75, v55, v56 offset0:156 offset1:222
	ds_write2_b32 v76, v57, v58 offset0:32 offset1:98
	ds_write2_b32 v76, v59, v60 offset0:164 offset1:230
	ds_write2_b32 v77, v61, v62 offset0:40 offset1:106
	ds_write2_b32 v77, v63, v64 offset0:172 offset1:238
	ds_write2_b32 v78, v65, v66 offset0:48 offset1:114
	ds_write2_b32 v78, v67, v68 offset0:180 offset1:246
	ds_write2_b32 v79, v69, v70 offset0:56 offset1:122
	ds_write2_b32 v79, v71, v72 offset0:188 offset1:254
	v_mov_b32_e32 v15, v3
	v_mov_b32_e32 v17, v3
	v_lshl_add_u64 v[28:29], s[0:1], 0, v[2:3]
	s_waitcnt lgkmcnt(0)
	v_lshl_add_u64 v[30:31], v[28:29], 0, v[14:15]
	v_lshl_add_u64 v[32:33], v[28:29], 0, v[16:17]
	ds_read_b32 v1, v34
	ds_read_b32 v5, v34 offset:132
	ds_read_b32 v7, v34 offset:264
	ds_read_b32 v9, v34 offset:396
	ds_read_b32 v11, v34 offset:528
	ds_read_b32 v13, v34 offset:660
	ds_read_b32 v15, v34 offset:792
	ds_read_b32 v17, v34 offset:924
	s_waitcnt lgkmcnt(0)
	v_cvt_pk_bf16_f32 v24, v1, v5
	v_cvt_pk_bf16_f32 v25, v7, v9
	v_cvt_pk_bf16_f32 v26, v11, v13
	v_mov_b32_e32 v19, v3
	v_cvt_pk_bf16_f32 v27, v15, v17
	flat_store_dwordx4 v[30:31], v[24:27]
	ds_read_b32 v1, v34 offset:32
	ds_read_b32 v5, v34 offset:164
	ds_read_b32 v7, v34 offset:296
	ds_read_b32 v9, v34 offset:428
	ds_read_b32 v11, v34 offset:560
	ds_read_b32 v13, v34 offset:692
	ds_read_b32 v15, v34 offset:824
	ds_read_b32 v17, v34 offset:956
	s_waitcnt lgkmcnt(0)
	v_cvt_pk_bf16_f32 v24, v1, v5
	v_cvt_pk_bf16_f32 v25, v7, v9
	v_cvt_pk_bf16_f32 v26, v11, v13
	v_lshl_add_u64 v[50:51], v[28:29], 0, v[18:19]
	v_cvt_pk_bf16_f32 v27, v15, v17
	flat_store_dwordx4 v[32:33], v[24:27]
	ds_read_b32 v1, v34 offset:64
	ds_read_b32 v5, v34 offset:196
	ds_read_b32 v7, v34 offset:328
	ds_read_b32 v9, v34 offset:460
	ds_read_b32 v11, v34 offset:592
	ds_read_b32 v13, v34 offset:724
	ds_read_b32 v15, v34 offset:856
	ds_read_b32 v17, v34 offset:988
	s_waitcnt lgkmcnt(0)
	v_cvt_pk_bf16_f32 v24, v1, v5
	v_cvt_pk_bf16_f32 v25, v7, v9
	v_cvt_pk_bf16_f32 v26, v11, v13
	v_mov_b32_e32 v21, v3
	v_cvt_pk_bf16_f32 v27, v15, v17
	flat_store_dwordx4 v[50:51], v[24:27]
	ds_read_b32 v1, v34 offset:96
	ds_read_b32 v5, v34 offset:228
	ds_read_b32 v7, v34 offset:360
	ds_read_b32 v9, v34 offset:492
	ds_read_b32 v11, v34 offset:624
	ds_read_b32 v13, v34 offset:756
	ds_read_b32 v15, v34 offset:888
	ds_read_b32 v17, v34 offset:1020
	v_lshl_add_u64 v[28:29], v[28:29], 0, v[20:21]
	s_waitcnt lgkmcnt(0)
	v_cvt_pk_bf16_f32 v24, v1, v5
	v_cvt_pk_bf16_f32 v25, v7, v9
	v_cvt_pk_bf16_f32 v26, v11, v13
	v_cvt_pk_bf16_f32 v27, v15, v17
	flat_store_dwordx4 v[28:29], v[24:27]
	s_waitcnt lgkmcnt(0)
	s_add_i32 s2, s8, 0x600
	s_add_i32 s7, s7, 0xc000
	s_cmpk_lt_i32 s8, 0xfb00
	s_mov_b32 s8, s2
	s_cbranch_scc1 .LBB0_1075
	v_mov_b32_e32 v3, 0
	v_readlane_b32 s16, v249, 1
	v_mov_b32_e32 v5, v3
	v_readlane_b32 s18, v249, 3
	v_readlane_b32 s19, v249, 4
	s_add_u32 s5, s68, 0x2100000
	s_addc_u32 s6, s69, 0
	v_lshl_add_u64 v[22:23], s[18:19], 0, v[4:5]
	s_mov_b32 s7, s100
	v_readlane_b32 s17, v249, 2
	v_readlane_b32 s20, v249, 5
	v_readlane_b32 s21, v249, 6
	v_readlane_b32 s22, v249, 7
	v_readlane_b32 s23, v249, 8
	v_readlane_b32 s24, v249, 9
	v_readlane_b32 s25, v249, 10
	v_readlane_b32 s26, v249, 11
	v_readlane_b32 s27, v249, 12
	v_readlane_b32 s28, v249, 13
	v_readlane_b32 s29, v249, 14
	v_readlane_b32 s30, v249, 15
	v_readlane_b32 s31, v249, 16
